# ph3 second-round units on WGs 32-63 plus attention loop: keep KV prefetch in flight across the staging writes (counted vmcnt instead of compiler's conservative vmcnt(0))
# baseline (speedup 1.0000x reference)
; __device__ __forceinline__ void partialSM(f32x16& p0, f32x16& p1, float& m_reg, float& mn, float& alpha) {
;   constexpr float C = SCALE * 1.4426950408889634f;
;   float pmax = p0[0]; for (int r = 1; r < 16; ++r) pmax = fmaxf(pmax, p0[r]); for (int r = 0; r < 16; ++r) pmax = fmaxf(pmax, p1[r]);
;   { auto rr = __builtin_amdgcn_permlane32_swap(__float_as_uint(pmax), __float_as_uint(pmax), false, false);
;     pmax = fmaxf(__uint_as_float(rr[0]), __uint_as_float(rr[1])); }
;   if (__builtin_expect(__all(pmax - m_reg <= THR / SCALE), 1)) { mn = m_reg; alpha = 1.f; }
;   else { mn = fmaxf(m_reg, pmax); alpha = __builtin_amdgcn_exp2f((m_reg - mn) * C); m_reg = mn; }
;   float mnC = -mn * C;
;   for (int r = 0; r < 16; ++r) p0[r] = fmaf(p0[r], C, mnC); for (int r = 0; r < 16; ++r) p1[r] = fmaf(p1[r], C, mnC);
;   for (int r = 0; r < 16; ++r) p0[r] = __builtin_amdgcn_exp2f(p0[r]);
; }
; __device__ __forceinline__ void finishSM(f32x16& p0, f32x16& p1, float alpha, float& l_reg, bf16x8& pa0, bf16x8& pa1, bf16x8& pa2, bf16x8& pa3) {
;   for (int r = 0; r < 16; ++r) p1[r] = __builtin_amdgcn_exp2f(p1[r]);
;   float ps = 0; for (int r = 0; r < 16; ++r) ps += p0[r]; for (int r = 0; r < 16; ++r) ps += p1[r];
;   { auto rr = __builtin_amdgcn_permlane32_swap(__float_as_uint(ps), __float_as_uint(ps), false, false);
;     ps = __uint_as_float(rr[0]) + __uint_as_float(rr[1]); }
;   l_reg = l_reg * alpha + ps;
;     ...
;   PK4(p0, 0, pa0); PK4(p0, 8, pa1); PK4(p1, 0, pa2); PK4(p1, 8, pa3);
;     ...
; }
; __device__ __forceinline__ void qkt(f32x16& p0, f32x16& p1, const bf16_t* Ks, const bf16x8* qr, int r32, int hi) {
;   p0 = f32x16{}; p1 = f32x16{};
; #pragma unroll
;   for (int d0 = 0; d0 < 4; ++d0) { int cb = (d0 * 16 + hi * 8) * 2;
;     bf16x8 b0 = *reinterpret_cast<const bf16x8*>((const char*)Ks + KSWZ(r32, cb));
;     bf16x8 b1 = *reinterpret_cast<const bf16x8*>((const char*)Ks + KSWZ(32 + r32, cb));
;     p0 = __builtin_amdgcn_mfma_f32_32x32x16_bf16(b0, qr[d0], p0, 0, 0, 0);
;     p1 = __builtin_amdgcn_mfma_f32_32x32x16_bf16(b1, qr[d0], p1, 0, 0, 0); }
; }
; __device__ __forceinline__ int v_st(int k, int c) { const int kk = (k & ~0xC) | ((k & 4) << 1) | ((k & 8) >> 1); return ((kk >> 3) * 4 + (c >> 5)) * 512 + ((kk & 7) * 32 + (c & 31)) * 2; }
.LBB0_169:
	ds_read_b64_tr_b16 v[176:177], v184 offset:0
	ds_read_b64_tr_b16 v[178:179], v184 offset:0x800
	ds_read_b64_tr_b16 v[200:201], v184 offset:0x1000
	ds_read_b64_tr_b16 v[202:203], v184 offset:0x1800
	ds_read_b64_tr_b16 v[204:205], v184 offset:0x2000
	ds_read_b64_tr_b16 v[206:207], v184 offset:0x2800
	ds_read_b64_tr_b16 v[208:209], v184 offset:0x3000
	ds_read_b64_tr_b16 v[210:211], v184 offset:0x3800
	s_waitcnt lgkmcnt(0)
	s_nop 0
	v_mfma_f32_32x32x16_bf16 v[0:15], v[136:139], v[176:179], v[0:15]
	ds_read_b64_tr_b16 v[176:177], v184 offset:0x200
	ds_read_b64_tr_b16 v[178:179], v184 offset:0xa00
	v_mfma_f32_32x32x16_bf16 v[0:15], v[140:143], v[200:203], v[0:15]
	ds_read_b64_tr_b16 v[200:201], v184 offset:0x1200
	ds_read_b64_tr_b16 v[202:203], v184 offset:0x1a00
	v_mfma_f32_32x32x16_bf16 v[0:15], v[144:147], v[204:207], v[0:15]
	ds_read_b64_tr_b16 v[204:205], v184 offset:0x2200
	ds_read_b64_tr_b16 v[206:207], v184 offset:0x2a00
	v_mfma_f32_32x32x16_bf16 v[0:15], v[148:151], v[208:211], v[0:15]
	ds_read_b64_tr_b16 v[208:209], v184 offset:0x3200
	ds_read_b64_tr_b16 v[210:211], v184 offset:0x3a00
	s_waitcnt lgkmcnt(0)
	v_mfma_f32_32x32x16_bf16 v[48:63], v[136:139], v[176:179], v[48:63]
	ds_read_b64_tr_b16 v[176:177], v184 offset:0x400
	ds_read_b64_tr_b16 v[178:179], v184 offset:0xc00
	v_mfma_f32_32x32x16_bf16 v[48:63], v[140:143], v[200:203], v[48:63]
	ds_read_b64_tr_b16 v[200:201], v184 offset:0x1400
	ds_read_b64_tr_b16 v[202:203], v184 offset:0x1c00
	v_mfma_f32_32x32x16_bf16 v[48:63], v[144:147], v[204:207], v[48:63]
	ds_read_b64_tr_b16 v[204:205], v184 offset:0x2400
	ds_read_b64_tr_b16 v[206:207], v184 offset:0x2c00
	v_mfma_f32_32x32x16_bf16 v[48:63], v[148:151], v[208:211], v[48:63]
	ds_read_b64_tr_b16 v[208:209], v184 offset:0x3400
	ds_read_b64_tr_b16 v[210:211], v184 offset:0x3c00
	s_waitcnt lgkmcnt(0)
	v_mfma_f32_32x32x16_bf16 v[32:47], v[136:139], v[176:179], v[32:47]
	ds_read_b64_tr_b16 v[176:177], v184 offset:0x600
	ds_read_b64_tr_b16 v[178:179], v184 offset:0xe00
	v_mfma_f32_32x32x16_bf16 v[32:47], v[140:143], v[200:203], v[32:47]
	ds_read_b64_tr_b16 v[200:201], v184 offset:0x1600
	ds_read_b64_tr_b16 v[202:203], v184 offset:0x1e00
	v_mfma_f32_32x32x16_bf16 v[32:47], v[144:147], v[204:207], v[32:47]
	ds_read_b64_tr_b16 v[204:205], v184 offset:0x2600
	ds_read_b64_tr_b16 v[206:207], v184 offset:0x2e00
	v_mfma_f32_32x32x16_bf16 v[32:47], v[148:151], v[208:211], v[32:47]
	ds_read_b64_tr_b16 v[208:209], v184 offset:0x3600
	ds_read_b64_tr_b16 v[210:211], v184 offset:0x3e00
	s_waitcnt lgkmcnt(0)
	v_mfma_f32_32x32x16_bf16 v[16:31], v[136:139], v[176:179], v[16:31]
	v_max_f32_e32 v136, v81, v81
	v_max_f32_e32 v137, v80, v80
	v_max_f32_e32 v136, v137, v136
	v_max3_f32 v136, v136, v82, v83
	v_max3_f32 v136, v136, v84, v85
	v_max3_f32 v136, v136, v86, v87
	v_max3_f32 v136, v136, v88, v89
	v_max3_f32 v136, v136, v90, v91
	v_max3_f32 v136, v136, v92, v93
	v_mfma_f32_32x32x16_bf16 v[16:31], v[140:143], v[200:203], v[16:31]
	v_max3_f32 v136, v136, v94, v95
	v_max3_f32 v136, v136, v64, v65
	v_max3_f32 v136, v136, v66, v67
	v_max3_f32 v136, v136, v68, v69
	v_max3_f32 v136, v136, v70, v71
	v_max3_f32 v136, v136, v72, v73
	v_max3_f32 v136, v136, v74, v75
	v_max3_f32 v136, v136, v76, v77
	v_mfma_f32_32x32x16_bf16 v[16:31], v[144:147], v[204:207], v[16:31]
	v_max3_f32 v136, v136, v78, v79
	v_mov_b32_e32 v137, v136
	s_nop 1
	v_permlane32_swap_b32_e32 v136, v137
	v_max_f32_e32 v137, v137, v137
	v_max_f32_e32 v136, v136, v136
	v_max_f32_e32 v136, v136, v137
	v_sub_f32_e32 v137, v136, v197
	v_cmp_ge_f32_e32 vcc, s24, v137
	v_max_f32_e32 v137, v197, v197
	v_max_f32_e32 v136, v137, v136
	v_mfma_f32_32x32x16_bf16 v[16:31], v[148:151], v[208:211], v[16:31]
	v_sub_f32_e32 v137, v197, v136
	v_mul_f32_e32 v137, 0x3e38aa3b, v137
	v_exp_f32_e32 v137, v137
	s_cmp_eq_u64 vcc, exec
	s_cselect_b64 s[40:41], -1, 0
	s_barrier
	s_waitcnt vmcnt(3)
	v_cndmask_b32_e64 v141, v137, 1.0, s[40:41]
	v_cmp_gt_f32_e32 vcc, 1.0, v141
	s_cmp_gt_u32 s26, 32
	s_cbranch_scc0 .Lattn_pf_inflight
	s_waitcnt vmcnt(0)
.Lattn_pf_inflight:
	ds_write_b128 v187, v[124:127] offset:16384
	ds_write_b128 v188, v[128:131] offset:16384
	ds_write_b128 v186, v[132:135] offset:40960
	s_cbranch_vccz .LBB0_173
	s_and_saveexec_b64 s[8:9], s[38:39]
	ds_write_b32 v182, v141 offset:49280
	s_or_b64 exec, exec, s[8:9]
	s_waitcnt lgkmcnt(0)
	v_add_u32_e32 v137, v171, v152
	ds_read_b128 v[124:127], v137 offset:49376
	ds_read_b128 v[128:131], v137 offset:49344
	ds_read_b128 v[132:135], v137 offset:49312
	ds_read_b128 v[142:145], v137 offset:49280
	s_waitcnt lgkmcnt(3)
	v_pk_mul_f32 v[12:13], v[12:13], v[124:125]
	s_waitcnt lgkmcnt(2)
	v_pk_mul_f32 v[8:9], v[8:9], v[128:129]
	s_waitcnt lgkmcnt(1)
	v_pk_mul_f32 v[4:5], v[4:5], v[132:133]
	v_pk_mul_f32 v[14:15], v[14:15], v[126:127]
	v_pk_mul_f32 v[10:11], v[10:11], v[130:131]
	v_pk_mul_f32 v[6:7], v[6:7], v[134:135]
	s_waitcnt lgkmcnt(0)
	v_pk_mul_f32 v[2:3], v[2:3], v[144:145]
	v_pk_mul_f32 v[0:1], v[0:1], v[142:143]
	v_pk_mul_f32 v[60:61], v[60:61], v[124:125]
	v_pk_mul_f32 v[56:57], v[56:57], v[128:129]
	v_pk_mul_f32 v[52:53], v[52:53], v[132:133]
	v_pk_mul_f32 v[62:63], v[62:63], v[126:127]
	v_pk_mul_f32 v[58:59], v[58:59], v[130:131]
	v_pk_mul_f32 v[54:55], v[54:55], v[134:135]
	v_pk_mul_f32 v[50:51], v[50:51], v[144:145]
	v_pk_mul_f32 v[48:49], v[48:49], v[142:143]
	v_pk_mul_f32 v[44:45], v[44:45], v[124:125]
	v_pk_mul_f32 v[40:41], v[40:41], v[128:129]
	v_pk_mul_f32 v[36:37], v[36:37], v[132:133]
	v_pk_mul_f32 v[46:47], v[46:47], v[126:127]
	v_pk_mul_f32 v[42:43], v[42:43], v[130:131]
	v_pk_mul_f32 v[38:39], v[38:39], v[134:135]
	v_pk_mul_f32 v[34:35], v[34:35], v[144:145]
	v_pk_mul_f32 v[32:33], v[32:33], v[142:143]
	v_pk_mul_f32 v[28:29], v[28:29], v[124:125]
	v_pk_mul_f32 v[24:25], v[24:25], v[128:129]
	v_pk_mul_f32 v[20:21], v[20:21], v[132:133]
	v_pk_mul_f32 v[30:31], v[30:31], v[126:127]
	v_pk_mul_f32 v[26:27], v[26:27], v[130:131]
	v_pk_mul_f32 v[22:23], v[22:23], v[134:135]
	v_pk_mul_f32 v[18:19], v[18:19], v[144:145]
	v_pk_mul_f32 v[16:17], v[16:17], v[142:143]

;     ...
;     for (;;) {
;         __syncthreads();
;         if (tid == 0) bc[0] = (int)__hip_atomic_fetch_add(ctr, (unsigned)NSTEAL, __ATOMIC_RELAXED, __HIP_MEMORY_SCOPE_AGENT);
;         __syncthreads();
;         const int base = bc[0];
;         if (base >= n) break;
;         const int j = base + w;
;         if (w < NSTEAL && j < n) convert_item(a, j < n1 ? lo1 + j : (j < n1 + n2 ? lo2 + (j - n1) : lo3 + (j - n1 - n2)), scr, lane);
.LBB0_372:
	s_or_b64 exec, exec, s[10:11]
	v_mov_b32_e32 v1, s23
	s_waitcnt lgkmcnt(0)
	s_barrier
	ds_read_b32 v1, v1
	s_movk_i32 s10, 0x3b00
	s_waitcnt lgkmcnt(0)
	v_cmp_gt_i32_e32 vcc, s10, v1
	v_readfirstlane_b32 s12, v1
	s_mov_b64 s[10:11], -1
	s_cbranch_vccz .LBB0_367
	s_add_i32 s12, s12, s4
	s_cmpk_lt_i32 s12, 0x3b00
	s_cselect_b64 s[10:11], -1, 0
	s_and_b64 s[10:11], s[8:9], s[10:11]
	s_andn2_b64 vcc, exec, s[10:11]
	s_cbranch_vccnz .LBB0_366
	s_cmpk_lt_u32 s12, 0x2b00
	s_movk_i32 s10, 0x35c0
	s_cselect_b32 s10, s10, 0x5600
	s_cmpk_gt_i32 s12, 0x203f
	s_cselect_b32 s10, s10, 0x2040
	s_add_i32 s12, s12, s10
	s_cmp_gt_i32 s12, 0x80ff
	s_mov_b64 s[10:11], -1
	s_cbranch_scc0 .LBB0_376
	s_add_i32 s10, s12, 0xffff7f00
	v_readlane_b32 s64, v248, 11
	s_lshr_b32 s10, s10, 1
	v_readlane_b32 s74, v248, 21
	v_readlane_b32 s75, v248, 22
	s_and_b32 s14, s10, 0x7fffffc0
	s_lshl_b32 s10, s12, 6
	v_readlane_b32 s68, v248, 15
	v_readlane_b32 s69, v248, 16
	v_readlane_b32 s76, v248, 23
	v_readlane_b32 s77, v248, 24
	v_readlane_b32 s79, v248, 26
	s_movk_i32 s74, 0x8000
	s_and_b32 s26, s10, 0x1fc0
	s_mov_b64 s[10:11], 0
	v_readlane_b32 s65, v248, 12
	v_readlane_b32 s66, v248, 13
	v_readlane_b32 s67, v248, 14
	v_readlane_b32 s70, v248, 17
	v_readlane_b32 s71, v248, 18
	v_readlane_b32 s72, v248, 19
	v_readlane_b32 s73, v248, 20
	v_readlane_b32 s78, v248, 25
	s_mov_b64 s[76:77], 0x800
	s_mov_b32 s75, -1
	s_mov_b32 s79, 0x800000
	s_mov_b64 s[18:19], s[68:69]

; __device__ __forceinline__ void convert_item(const Args& a, int it, LAS float* scr, int lane) {
;     ...
;         if (it < T_FFN) { const int m = it / 2752, r = it % 2752, f = m / 3, kind = m % 3;
;             if (kind < 2) { k0 = (r / 86) * 64; n0 = (r % 86) * 64; src = a.in[kind ? I_WU : I_WG] + (size_t)f * DM * DFF; ldn = DFF; Kd = DM; dst = WGU + (size_t)f * 2 * DFF * DM; drow = (n0 >> 7) * 256 + kind * 128 + (n0 & 127); }
;             else { k0 = (r / 32) * 64; n0 = (r % 32) * 64; src = a.in[I_WDN] + (size_t)f * DFF * DM; ldn = DM; Kd = DFF; dst = WD + (size_t)f * DM * DFF; drow = n0; }
;     ...
;     for (;;) {
;         __syncthreads();
;         if (tid == 0) bc[0] = (int)__hip_atomic_fetch_add(ctr, (unsigned)NSTEAL, __ATOMIC_RELAXED, __HIP_MEMORY_SCOPE_AGENT);
;         __syncthreads();
;         const int base = bc[0];
;         if (base >= n) break;
;         const int j = base + w;
;         if (w < NSTEAL && j < n) convert_item(a, j < n1 ? lo1 + j : (j < n1 + n2 ? lo2 + (j - n1) : lo3 + (j - n1 - n2)), scr, lane);
.LBB0_471:
	s_or_b64 exec, exec, s[10:11]
	v_mov_b32_e32 v1, s23
	s_waitcnt lgkmcnt(0)
	s_barrier
	ds_read_b32 v1, v1
	s_movk_i32 s10, 0xabf
	s_waitcnt lgkmcnt(0)
	v_cmp_lt_i32_e32 vcc, s10, v1
	v_readfirstlane_b32 s12, v1
	s_mov_b64 s[10:11], -1
	s_cbranch_vccnz .LBB0_466
	s_add_i32 s10, s12, s4
	s_cmpk_lt_i32 s10, 0xac0
	s_cselect_b64 s[12:13], -1, 0
	s_and_b64 s[12:13], s[8:9], s[12:13]
	s_andn2_b64 vcc, exec, s[12:13]
	s_cbranch_vccnz .LBB0_465
	s_addk_i32 s10, 0x60c0
	s_mul_hi_i32 s11, s10, 0x2fa0be83
	s_lshr_b32 s12, s11, 31
	s_ashr_i32 s11, s11, 9
	s_add_i32 s11, s11, s12
	s_mul_i32 s12, s11, 0xac0
	s_sub_i32 s16, s10, s12
	s_mul_hi_i32 s10, s10, 0xfe03f81
	s_lshr_b32 s12, s10, 31
	s_ashr_i32 s28, s10, 9
	s_mul_hi_i32 s10, s11, 0x55555556
	s_add_i32 s28, s28, s12
	s_lshr_b32 s12, s10, 31
	s_add_i32 s10, s10, s12
	s_mul_i32 s10, s10, 3
	s_sub_i32 s15, s11, s10
	s_cmp_gt_i32 s15, 1
	s_mov_b64 s[10:11], -1
	s_sext_i32_i16 s26, s16
	s_mul_hi_i32 s17, s28, 0x2b00000
	s_mul_i32 s27, s28, 0x2b00000
	s_cbranch_scc0 .LBB0_475
	s_bfe_u32 s10, s26, 0x5001a
	s_add_i32 s10, s16, s10
	s_sext_i32_i16 s11, s10
	s_and_b32 s10, s10, 0xffe0
	s_sub_i32 s10, s16, s10
	s_sext_i32_i16 s10, s10
	v_readlane_b32 s64, v248, 11
	s_lshr_b32 s14, s11, 5
	s_lshl_b32 s25, s10, 6
	v_readlane_b32 s66, v248, 13
	v_readlane_b32 s67, v248, 14
	s_add_u32 s18, s66, s27
	s_addc_u32 s19, s67, s17
	s_mul_hi_i32 s10, s28, 0x1580000
	s_mul_i32 s28, s28, 0x1580000
	v_readlane_b32 s11, v248, 40
	s_add_u32 s12, s11, s28
	v_readlane_b32 s11, v248, 41
	v_readlane_b32 s65, v248, 12
	v_readlane_b32 s68, v248, 15
	v_readlane_b32 s69, v248, 16
	v_readlane_b32 s70, v248, 17
	v_readlane_b32 s71, v248, 18
	v_readlane_b32 s72, v248, 19
	v_readlane_b32 s73, v248, 20
	v_readlane_b32 s74, v248, 21
	v_readlane_b32 s75, v248, 22
	v_readlane_b32 s76, v248, 23
	v_readlane_b32 s77, v248, 24
	v_readlane_b32 s78, v248, 25
	v_readlane_b32 s79, v248, 26
	s_addc_u32 s13, s11, s10
	s_mov_b64 s[10:11], 0
